# attention static priority raise moved from waves 4-7 to waves 0-3
# speedup vs baseline: 1.0008x; 1.0008x over previous
; __global__ void __launch_bounds__(512, 2) fwd_megakernel(Args args) {
;     ...
;             if (__builtin_amdgcn_readfirstlane(threadIdx.x) >= 256) __builtin_amdgcn_s_setprio(1);
.LBB0_183:
	v_readfirstlane_b32 s4, v214
	s_cmpk_gt_i32 s4, 0xff
	s_cbranch_scc1 .LBB0_185
	s_setprio 1
